# v15 + attention main loop: steps open with their first QK MFMA
# baseline (speedup 1.0000x reference)
.LBB0_830:
	v_lshlrev_b32_e32 v0, 1, v204
	v_lshrrev_b32_e32 v2, 2, v204
	v_and_b32_e32 v209, 32, v0
	v_lshlrev_b32_e32 v211, 3, v204
	v_and_or_b32 v2, v2, 3, v212
	v_add_u32_e32 v0, 0, v209
	v_and_b32_e32 v210, 24, v211
	v_lshlrev_b32_e32 v208, 6, v2
	v_add3_u32 v217, v0, v210, v208
	v_max3_f32 v0, v48, v49, v32
	v_max3_f32 v2, v50, v51, v33
	s_add_i32 s6, s83, s93
	v_max3_f32 v0, v0, v34, v35
	v_max3_f32 v2, v2, v54, v55
	s_add_i32 s1, s13, 0x100
	v_max3_f32 v0, v0, v52, v53
	v_max3_f32 v2, v2, v38, v39
	s_lshr_b32 s1, s1, 6
	v_max3_f32 v0, v0, v36, v37
	v_max3_f32 v2, v2, v58, v59
	v_lshl_add_u32 v207, v212, 2, s87
	v_max3_f32 v0, v0, v56, v57
	v_max3_f32 v2, v2, v42, v43
	s_mov_b32 s10, 1
	v_max3_f32 v0, v0, v40, v41
	v_max3_f32 v2, v2, v62, v63
	s_mov_b32 s23, 0
	v_max3_f32 v0, v0, v60, v61
	v_max3_f32 v2, v2, v46, v47
	s_andn2_b64 vcc, exec, s[4:5]
	v_max3_f32 v0, v0, v44, v45
	v_cmp_gt_u32_e64 s[4:5], 32, v204
	v_max_f32_e32 v0, v0, v2
	s_nop 0
	v_mov_b32_e32 v2, v0
	s_nop 1
	v_permlane32_swap_b32_e32 v0, v2
	v_max_f32_e32 v0, v0, v2
	s_nop 0
	v_add_f32_e32 v215, v1, v0
	v_sub_f32_e32 v2, v48, v0
	v_sub_f32_e32 v3, v32, v0
	v_sub_f32_e32 v4, v49, v0
	v_sub_f32_e32 v5, v33, v0
	v_sub_f32_e32 v6, v50, v0
	s_nop 0
	v_xor_b32_e32 v64, 0x80000000, v215
	v_mov_b32_e32 v65, v64
	v_mov_b32_e32 v66, v64
	v_mov_b32_e32 v67, v64
	v_mov_b32_e32 v68, v64
	v_mov_b32_e32 v69, v64
	v_mov_b32_e32 v70, v64
	v_mov_b32_e32 v71, v64
	v_mov_b32_e32 v72, v64
	v_mov_b32_e32 v73, v64
	v_mov_b32_e32 v74, v64
	v_mov_b32_e32 v75, v64
	v_mov_b32_e32 v76, v64
	v_mov_b32_e32 v77, v64
	v_mov_b32_e32 v78, v64
	v_mov_b32_e32 v79, v64
	s_waitcnt vmcnt(0) lgkmcnt(0)
	s_barrier
	s_mov_b32 m0, s6
	s_nop 0
	global_load_lds_dwordx4 v216, s[38:39]
	s_add_i32 s6, s84, s93
	s_mov_b32 m0, s6
	s_nop 0
	global_load_lds_dwordx4 v216, s[40:41]
	s_add_i32 s6, s78, 0xe000
	s_mov_b32 m0, s6
	s_nop 0
	global_load_lds_dwordx4 v216, s[42:43]
	ds_read_b128 v[196:199], v214 offset:12288
	ds_read_b128 v[184:187], v214 offset:12800
	ds_read_b128 v[188:191], v214 offset:14336
	ds_read_b128 v[192:195], v214 offset:14848
	v_sub_f32_e32 v7, v34, v0
	v_sub_f32_e32 v8, v51, v0
	v_sub_f32_e32 v9, v35, v0
	v_sub_f32_e32 v10, v52, v0
	v_sub_f32_e32 v11, v36, v0
	v_sub_f32_e32 v12, v53, v0
	v_sub_f32_e32 v13, v37, v0
	v_sub_f32_e32 v14, v54, v0
	v_sub_f32_e32 v15, v38, v0
	v_sub_f32_e32 v32, v55, v0
	v_sub_f32_e32 v33, v39, v0
	v_sub_f32_e32 v34, v56, v0
	v_sub_f32_e32 v35, v40, v0
	v_sub_f32_e32 v36, v57, v0
	v_sub_f32_e32 v37, v41, v0
	v_sub_f32_e32 v38, v58, v0
	v_sub_f32_e32 v39, v42, v0
	v_sub_f32_e32 v40, v59, v0
	v_sub_f32_e32 v41, v43, v0
	v_sub_f32_e32 v42, v60, v0
	v_sub_f32_e32 v43, v44, v0
	v_sub_f32_e32 v44, v61, v0
	v_sub_f32_e32 v45, v45, v0
	v_sub_f32_e32 v48, v62, v0
	v_sub_f32_e32 v46, v46, v0
	v_sub_f32_e32 v49, v63, v0
	v_sub_f32_e32 v0, v47, v0
	v_exp_f32_e32 v96, v2
	v_exp_f32_e32 v97, v4
	v_exp_f32_e32 v98, v6
	v_exp_f32_e32 v99, v8
	v_exp_f32_e32 v100, v10
	v_exp_f32_e32 v101, v12
	v_exp_f32_e32 v102, v14
	v_exp_f32_e32 v103, v32
	v_exp_f32_e32 v104, v34
	v_exp_f32_e32 v105, v36
	v_exp_f32_e32 v106, v38
	v_exp_f32_e32 v107, v40
	v_exp_f32_e32 v108, v42
	v_exp_f32_e32 v109, v44
	v_exp_f32_e32 v110, v48
	v_exp_f32_e32 v111, v49
	v_exp_f32_e32 v80, v3
	v_exp_f32_e32 v81, v5
	v_exp_f32_e32 v82, v7
	v_exp_f32_e32 v83, v9
	v_exp_f32_e32 v84, v11
	v_exp_f32_e32 v85, v13
	v_exp_f32_e32 v86, v15
	v_exp_f32_e32 v87, v33
	v_exp_f32_e32 v88, v35
	v_exp_f32_e32 v89, v37
	v_exp_f32_e32 v90, v39
	v_exp_f32_e32 v91, v41
	v_exp_f32_e32 v92, v43
	v_exp_f32_e32 v93, v45
	v_exp_f32_e32 v94, v46
	v_exp_f32_e32 v95, v0
	s_cbranch_vccnz .LBB0_846
	v_mov_b32_e32 v14, v1
	v_mov_b32_e32 v15, v1
	v_mov_b32_e32 v0, v1
	v_mov_b32_e32 v2, v1
	v_mov_b32_e32 v3, v1
	v_mov_b32_e32 v4, v1
	v_mov_b32_e32 v5, v1
	v_mov_b32_e32 v6, v1
	v_mov_b32_e32 v7, v1
	v_mov_b32_e32 v8, v1
	v_mov_b32_e32 v9, v1
	v_mov_b32_e32 v10, v1
	v_mov_b32_e32 v11, v1
	v_mov_b32_e32 v12, v1
	v_mov_b32_e32 v13, v1
	v_mov_b64_e32 v[62:63], v[14:15]
	v_mov_b64_e32 v[46:47], v[14:15]
	s_add_i32 s66, s1, -5
	v_lshl_add_u32 v219, v205, 2, s87
	s_mov_b32 s62, 0
	s_movk_i32 s23, 0x4000
	s_movk_i32 s10, 0x2000
	v_mov_b32_e32 v218, 0
	s_mov_b32 s67, 4
	s_mov_b64 s[6:7], s[52:53]
	s_mov_b64 s[58:59], s[50:51]
	s_mov_b64 s[60:61], s[48:49]
	v_mov_b64_e32 v[60:61], v[12:13]
	v_mov_b64_e32 v[58:59], v[10:11]
	v_mov_b64_e32 v[56:57], v[8:9]
	v_mov_b64_e32 v[54:55], v[6:7]
	v_mov_b64_e32 v[52:53], v[4:5]
	v_mov_b64_e32 v[50:51], v[2:3]
	v_mov_b64_e32 v[48:49], v[0:1]
	v_mov_b64_e32 v[44:45], v[12:13]
	v_mov_b64_e32 v[42:43], v[10:11]
	v_mov_b64_e32 v[40:41], v[8:9]
	v_mov_b64_e32 v[38:39], v[6:7]
	v_mov_b64_e32 v[36:37], v[4:5]
	v_mov_b64_e32 v[34:35], v[2:3]
	v_mov_b64_e32 v[32:33], v[0:1]
	s_waitcnt lgkmcnt(0)
.LBB0_832:
	v_mfma_f32_32x32x16_bf16 v[128:143], v[196:199], v[176:179], v[64:79]
	v_cvt_pk_bf16_f32 v172, v104, v105
	v_cvt_pk_bf16_f32 v180, v96, v97
	s_add_i32 s12, s67, -3
	s_and_b32 s22, s12, 3
	s_mulk_i32 s22, 0x3000
	v_add_u32_e32 v0, s22, v214
	ds_read_b128 v[2:5], v0 offset:4096
	v_add_u32_e32 v14, s62, v217
	s_waitcnt lgkmcnt(4)
	v_add_f32_e32 v6, v96, v97
	v_add_f32_e32 v6, v98, v6
	v_add_f32_e32 v6, v99, v6
	v_add_f32_e32 v10, v100, v6
	ds_read_b128 v[6:9], v0 offset:4608
	s_waitcnt lgkmcnt(4)
	v_mfma_f32_32x32x16_bf16 v[112:127], v[184:187], v[176:179], v[64:79]
	v_add_f32_e32 v10, v101, v10
	v_add_f32_e32 v10, v102, v10
	v_add_f32_e32 v15, v103, v10
	v_cvt_pk_bf16_f32 v181, v98, v99
	s_add_u32 s62, s58, 0xffff0000
	s_addc_u32 s63, s59, -1
	s_and_b32 s12, s67, 3
	s_mulk_i32 s12, 0x3000
	s_add_i32 s64, s12, s78
	s_mov_b32 m0, s64
	s_nop 0
	global_load_lds_dwordx4 v216, s[62:63]
	ds_read_b128 v[10:13], v0 offset:6144
	s_waitcnt lgkmcnt(4)
	v_mfma_f32_32x32x16_bf16 v[128:143], v[188:191], v[168:171], v[128:143]
	v_add_f32_e32 v15, v104, v15
	v_add_f32_e32 v15, v105, v15
	v_add_f32_e32 v15, v106, v15
	v_cvt_pk_bf16_f32 v182, v100, v101
	ds_read_b128 v[96:99], v0 offset:6656
	s_waitcnt lgkmcnt(4)
	v_mfma_f32_32x32x16_bf16 v[112:127], v[192:195], v[168:171], v[112:127]
	v_add_f32_e32 v15, v107, v15
	v_add_f32_e32 v15, v108, v15
	v_add_f32_e32 v15, v109, v15
	v_cvt_pk_bf16_f32 v183, v102, v103
	s_add_u32 s62, s60, 0xfffff000
	s_addc_u32 s63, s61, -1
	s_add_i32 s12, s12, s85
	s_mov_b32 m0, s12
	s_nop 0
	global_load_lds_dwordx4 v216, s[62:63]
	ds_read_b128 v[100:103], v0 offset:8192
	s_waitcnt lgkmcnt(4)
	v_mfma_f32_32x32x16_bf16 v[128:143], v[2:5], v[164:167], v[128:143]
	v_add_f32_e32 v15, v110, v15
	v_add_f32_e32 v15, v111, v15
	v_add_f32_e32 v15, v80, v15
	ds_read_b128 v[2:5], v0 offset:8704
	s_waitcnt lgkmcnt(4)
	v_mfma_f32_32x32x16_bf16 v[112:127], v[6:9], v[164:167], v[112:127]
	v_add_f32_e32 v15, v81, v15
	v_add_f32_e32 v15, v82, v15
	v_add_f32_e32 v15, v83, v15
	v_cvt_pk_bf16_f32 v173, v106, v107
	s_add_u32 s62, s6, 0xffff0000
	s_addc_u32 s63, s7, -1
	s_add_i32 s12, s23, s86
	s_mov_b32 m0, s12
	s_nop 0
	global_load_lds_dwordx4 v216, s[62:63]
	ds_read_b128 v[104:107], v0 offset:10240
	s_waitcnt lgkmcnt(4)
	v_mfma_f32_32x32x16_bf16 v[128:143], v[10:13], v[156:159], v[128:143]
	v_add_f32_e32 v6, v84, v15
	v_add_f32_e32 v6, v85, v6
	v_cvt_pk_bf16_f32 v174, v108, v109
	v_cvt_pk_bf16_f32 v175, v110, v111
	ds_read_b128 v[108:111], v0 offset:10752
	s_waitcnt lgkmcnt(4)
	v_mfma_f32_32x32x16_bf16 v[112:127], v[96:99], v[156:159], v[112:127]
	v_add_f32_e32 v0, v86, v6
	v_add_f32_e32 v0, v87, v0
	v_cvt_pk_bf16_f32 v160, v80, v81
	v_cvt_pk_bf16_f32 v161, v82, v83
	ds_read_b64_tr_b16 v[6:7], v14 offset:49152
	ds_read_b64_tr_b16 v[8:9], v14 offset:49664
	s_waitcnt lgkmcnt(5)
	v_mfma_f32_32x32x16_bf16 v[128:143], v[100:103], v[148:151], v[128:143]
	v_add_f32_e32 v0, v88, v0
	v_add_f32_e32 v0, v89, v0
	v_cvt_pk_bf16_f32 v162, v84, v85
	v_cvt_pk_bf16_f32 v163, v86, v87
	ds_read_b64_tr_b16 v[10:11], v14 offset:53248
	ds_read_b64_tr_b16 v[12:13], v14 offset:53760
	s_waitcnt lgkmcnt(6)
	v_mfma_f32_32x32x16_bf16 v[112:127], v[2:5], v[148:151], v[112:127]
	v_add_f32_e32 v0, v90, v0
	v_add_f32_e32 v0, v91, v0
	v_cvt_pk_bf16_f32 v152, v88, v89
	v_cvt_pk_bf16_f32 v153, v90, v91
	ds_read_b64_tr_b16 v[80:81], v14 offset:50176
	ds_read_b64_tr_b16 v[82:83], v14 offset:50688
	s_waitcnt lgkmcnt(7)
	v_mfma_f32_32x32x16_bf16 v[128:143], v[104:107], v[144:147], v[128:143]
	v_add_f32_e32 v0, v92, v0
	v_add_f32_e32 v0, v93, v0
	v_cvt_pk_bf16_f32 v154, v92, v93
	ds_read_b64_tr_b16 v[2:3], v14 offset:54272
	ds_read_b64_tr_b16 v[4:5], v14 offset:54784
	s_waitcnt lgkmcnt(8)
	v_mfma_f32_32x32x16_bf16 v[112:127], v[108:111], v[144:147], v[112:127]
	v_add_f32_e32 v0, v94, v0
	v_add_f32_e32 v0, v95, v0
	v_cvt_pk_bf16_f32 v155, v94, v95
	s_nop 1
	v_max_f32_e32 v15, v128, v129
	s_add_i32 s12, s67, -2
	s_and_b32 s12, s12, 3
	s_mulk_i32 s12, 0x3000
	s_nop 2
	v_max3_f32 v84, v130, v131, v113
	v_max3_f32 v15, v15, v112, v114
	v_max3_f32 v15, v15, v115, v132
	v_max3_f32 v84, v84, v134, v135
	v_max3_f32 v15, v15, v133, v116
	v_max3_f32 v84, v84, v118, v119
	v_max3_f32 v15, v15, v117, v136
	v_max3_f32 v84, v84, v138, v139
	v_max3_f32 v15, v15, v137, v120
	v_max3_f32 v84, v84, v122, v123
	v_max3_f32 v15, v15, v121, v140
	v_max3_f32 v84, v84, v142, v143
	v_max3_f32 v15, v15, v141, v124
	v_max3_f32 v84, v84, v126, v127
	v_max3_f32 v15, v15, v125, v84
	v_mov_b32_e32 v84, v15
	s_nop 1
	v_permlane32_swap_b32_e32 v15, v84
	v_max_f32_e32 v15, v15, v84
	v_cmp_lt_f32_e32 vcc, s94, v15
	s_cmp_lg_u64 vcc, 0
	v_add_f32_e32 v0, v218, v0
	s_cselect_b64 s[62:63], -1, 0
	s_cbranch_vccnz .LBB0_840

.LBB0_835:
	v_mfma_f32_32x32x16_bf16 v[96:111], v[2:5], v[176:179], v[64:79]
	s_add_i32 s12, s23, 0x2000
	s_cmpk_lg_i32 s23, 0x4000
	s_cselect_b32 s12, s12, 0
	ds_read_b128 v[188:191], v15 offset:4096
	v_add_u32_e32 v14, s10, v217
	s_waitcnt lgkmcnt(4)
	v_add_f32_e32 v80, v128, v129
	v_add_f32_e32 v80, v130, v80
	v_add_f32_e32 v80, v131, v80
	v_add_f32_e32 v80, v132, v80
	v_cvt_pk_bf16_f32 v180, v128, v129
	ds_read_b128 v[2:5], v15 offset:4608
	v_add_f32_e32 v80, v133, v80
	v_add_f32_e32 v80, v134, v80
	v_add_f32_e32 v128, v135, v80
	s_waitcnt lgkmcnt(4)
	v_mfma_f32_32x32x16_bf16 v[80:95], v[6:9], v[176:179], v[64:79]
	v_cvt_pk_bf16_f32 v181, v130, v131
	s_add_i32 s10, s22, s78
	s_mov_b32 m0, s10
	s_nop 0
	global_load_lds_dwordx4 v216, s[58:59]
	ds_read_b128 v[6:9], v15 offset:6144
	s_waitcnt lgkmcnt(4)
	v_mfma_f32_32x32x16_bf16 v[96:111], v[10:13], v[168:171], v[96:111]
	v_add_f32_e32 v128, v136, v128
	v_add_f32_e32 v128, v137, v128
	v_add_f32_e32 v128, v138, v128
	v_cvt_pk_bf16_f32 v182, v132, v133
	ds_read_b128 v[10:13], v15 offset:6656
	s_waitcnt lgkmcnt(4)
	v_mfma_f32_32x32x16_bf16 v[80:95], v[184:187], v[168:171], v[80:95]
	v_add_f32_e32 v128, v139, v128
	v_add_f32_e32 v128, v140, v128
	v_add_f32_e32 v132, v141, v128
	v_cvt_pk_bf16_f32 v183, v134, v135
	s_add_i32 s10, s22, s85
	s_mov_b32 m0, s10
	s_nop 0
	global_load_lds_dwordx4 v216, s[60:61]
	ds_read_b128 v[128:131], v15 offset:8192
	s_waitcnt lgkmcnt(4)
	v_mfma_f32_32x32x16_bf16 v[96:111], v[188:191], v[164:167], v[96:111]
	v_add_f32_e32 v132, v142, v132
	v_add_f32_e32 v132, v143, v132
	v_add_f32_e32 v152, v112, v132
	v_cvt_pk_bf16_f32 v172, v136, v137
	ds_read_b128 v[132:135], v15 offset:8704
	s_waitcnt lgkmcnt(4)
	v_mfma_f32_32x32x16_bf16 v[80:95], v[2:5], v[164:167], v[80:95]
	v_add_f32_e32 v136, v113, v152
	v_add_f32_e32 v136, v114, v136
	v_add_f32_e32 v136, v115, v136
	v_cvt_pk_bf16_f32 v173, v138, v139
	s_add_i32 s10, s12, s86
	s_mov_b32 m0, s10
	s_nop 0
	global_load_lds_dwordx4 v216, s[6:7]
	ds_read_b128 v[2:5], v15 offset:10240
	s_waitcnt lgkmcnt(4)
	v_mfma_f32_32x32x16_bf16 v[96:111], v[6:9], v[156:159], v[96:111]
	v_add_f32_e32 v136, v116, v136
	v_add_f32_e32 v152, v117, v136
	v_cvt_pk_bf16_f32 v174, v140, v141
	v_cvt_pk_bf16_f32 v175, v142, v143
	ds_read_b128 v[136:139], v15 offset:10752
	s_waitcnt lgkmcnt(4)
	v_mfma_f32_32x32x16_bf16 v[80:95], v[10:13], v[156:159], v[80:95]
	v_add_f32_e32 v6, v118, v152
	v_add_f32_e32 v6, v119, v6
	v_cvt_pk_bf16_f32 v160, v112, v113
	v_cvt_pk_bf16_f32 v161, v114, v115
	ds_read_b64_tr_b16 v[112:113], v14 offset:49152
	ds_read_b64_tr_b16 v[114:115], v14 offset:49664
	s_waitcnt lgkmcnt(5)
	v_mfma_f32_32x32x16_bf16 v[96:111], v[128:131], v[148:151], v[96:111]
	v_add_f32_e32 v6, v120, v6
	v_add_f32_e32 v6, v121, v6
	v_cvt_pk_bf16_f32 v162, v116, v117
	v_cvt_pk_bf16_f32 v163, v118, v119
	ds_read_b64_tr_b16 v[10:11], v14 offset:53248
	ds_read_b64_tr_b16 v[12:13], v14 offset:53760
	s_waitcnt lgkmcnt(6)
	v_mfma_f32_32x32x16_bf16 v[80:95], v[132:135], v[148:151], v[80:95]
	v_add_f32_e32 v6, v122, v6
	v_add_f32_e32 v15, v123, v6
	v_cvt_pk_bf16_f32 v152, v120, v121
	v_cvt_pk_bf16_f32 v153, v122, v123
	ds_read_b64_tr_b16 v[6:7], v14 offset:50176
	ds_read_b64_tr_b16 v[8:9], v14 offset:50688
	s_waitcnt lgkmcnt(7)
	v_mfma_f32_32x32x16_bf16 v[96:111], v[2:5], v[144:147], v[96:111]
	v_add_f32_e32 v15, v124, v15
	v_add_f32_e32 v15, v125, v15
	v_cvt_pk_bf16_f32 v154, v124, v125
	ds_read_b64_tr_b16 v[2:3], v14 offset:54272
	ds_read_b64_tr_b16 v[4:5], v14 offset:54784
	s_waitcnt lgkmcnt(8)
	v_mfma_f32_32x32x16_bf16 v[80:95], v[136:139], v[144:147], v[80:95]
	v_add_f32_e32 v15, v126, v15
	v_add_f32_e32 v15, v127, v15
	v_cvt_pk_bf16_f32 v155, v126, v127
	s_nop 1
	v_max_f32_e32 v116, v96, v97
	s_add_i32 s10, s67, -1
	s_and_b32 s22, s10, 3
	s_mulk_i32 s22, 0x3000
	s_nop 2
	v_max3_f32 v117, v98, v99, v81
	v_max3_f32 v116, v116, v80, v82
	v_max3_f32 v116, v116, v83, v100
	v_max3_f32 v117, v117, v102, v103
	v_max3_f32 v116, v116, v101, v84
	v_max3_f32 v117, v117, v86, v87
	v_max3_f32 v116, v116, v85, v104
	v_max3_f32 v117, v117, v106, v107
	v_max3_f32 v116, v116, v105, v88
	v_max3_f32 v117, v117, v90, v91
	v_max3_f32 v116, v116, v89, v108
	v_max3_f32 v117, v117, v110, v111
	v_max3_f32 v116, v116, v109, v92
	v_max3_f32 v117, v117, v94, v95
	v_add_f32_e32 v218, v0, v15
	v_max3_f32 v0, v116, v93, v117
	v_mov_b32_e32 v15, v0
	s_nop 1
	v_permlane32_swap_b32_e32 v0, v15
	v_max_f32_e32 v0, v0, v15
	v_cmp_lt_f32_e32 vcc, s94, v0
	s_cmp_lg_u64 vcc, 0
	s_cselect_b64 s[62:63], -1, 0
	s_cbranch_vccnz .LBB0_843
